# FFN2-down epilogue: counted waits on the first residual batch (vmcnt(8) then vmcnt(12)) instead of a full wait
# speedup vs baseline: 1.0002x; 1.0002x over previous
; #define ER_LOAD(q, buf) do { _Pragma("unroll") for (int mm = 0; mm < 2; ++mm) { const size_t off_ = (size_t)(row0 + ((q) >> 1) * HALF + (2 * ((q) & 1) + mm) * 16) * ldc + col0; \
;             _Pragma("unroll") for (int bj = 0; bj < 2; ++bj) _Pragma("unroll") for (int n = 0; n < 2; ++n) pre[buf][mm][bj][n] = *(const f32x4*)(base + off_ + bj * HALF + n * 16); } } while (0)
;     __device__ __forceinline__ void operator()(const f32x4 (&acc)[2][2][4][2], const Unit& u, int wr, int wc, int fr, int fq) const {
;     ...
;         ER_LOAD(0, 0);
; #pragma unroll
;         for (int q = 0; q < 4; ++q) {
;             if (q == 0) ER_LOAD(1, 1); else if (q == 1) ER_LOAD(2, 0); else if (q == 2) ER_LOAD(3, 1);
; #pragma unroll
;             for (int mm = 0; mm < 2; ++mm) { const int ai = q >> 1, m = 2 * (q & 1) + mm; const size_t off = (size_t)(row0 + ai * HALF + m * 16) * ldc + col0; float ss = 0.f;
;                 const int rl = wr * 64 + fr + ai * HALF + m * 16, cl0 = col0; const size_t xoff = (size_t)u.pm * ((size_t)ldc * BM) + (size_t)rl * 64;
; #pragma unroll
;                 for (int bj = 0; bj < 2; ++bj)
; #pragma unroll
;                     for (int n = 0; n < 2; ++n) {
;                         const f32x4 o = pre[q & 1][mm][bj][n] + acc[ai][bj][m][n] * scale;
;                         *(f32x4*)(out + off + bj * HALF + n * 16) = o;
.LBB0_1250:
	v_lshl_or_b32 v142, s55, 8, v155
	v_lshl_add_u32 v146, s54, 8, v1
	v_ashrrev_i32_e32 v143, 31, v142
	v_lshlrev_b64 v[142:143], 2, v[142:143]
	v_ashrrev_i32_e32 v147, 31, v146
	v_lshl_add_u64 v[144:145], s[48:49], 0, v[142:143]
	v_lshlrev_b64 v[148:149], 14, v[146:147]
	v_or_b32_e32 v172, 16, v146
	v_lshl_add_u64 v[168:169], v[144:145], 0, v[148:149]
	v_ashrrev_i32_e32 v173, 31, v172
	global_load_dwordx4 v[150:153], v[168:169], off
	global_load_dwordx4 v[160:163], v[168:169], off offset:64
	global_load_dwordx4 v[164:167], v[168:169], off offset:512
	s_nop 0
	global_load_dwordx4 v[168:171], v[168:169], off offset:576
	v_lshlrev_b64 v[220:221], 14, v[172:173]
	v_lshl_add_u64 v[184:185], v[144:145], 0, v[220:221]
	v_or_b32_e32 v188, 32, v146
	global_load_dwordx4 v[172:175], v[184:185], off
	global_load_dwordx4 v[176:179], v[184:185], off offset:64
	global_load_dwordx4 v[180:183], v[184:185], off offset:512
	s_nop 0
	global_load_dwordx4 v[184:187], v[184:185], off offset:576
	v_ashrrev_i32_e32 v189, 31, v188
	v_lshlrev_b64 v[222:223], 14, v[188:189]
	v_or_b32_e32 v146, 48, v146
	v_lshl_add_u64 v[200:201], v[144:145], 0, v[222:223]
	v_ashrrev_i32_e32 v147, 31, v146
	global_load_dwordx4 v[188:191], v[200:201], off
	global_load_dwordx4 v[192:195], v[200:201], off offset:64
	global_load_dwordx4 v[196:199], v[200:201], off offset:512
	s_nop 0
	global_load_dwordx4 v[200:203], v[200:201], off offset:576
	v_lshlrev_b64 v[224:225], 14, v[146:147]
	v_lshl_add_u64 v[146:147], v[144:145], 0, v[224:225]
	global_load_dwordx4 v[204:207], v[146:147], off
	global_load_dwordx4 v[208:211], v[146:147], off offset:64
	global_load_dwordx4 v[212:215], v[146:147], off offset:512
	global_load_dwordx4 v[216:219], v[146:147], off offset:576
	v_lshl_add_u64 v[146:147], s[48:49], 0, v[148:149]
	v_lshl_add_u64 v[146:147], v[146:147], 0, v[142:143]
	s_mov_b64 s[22:23], -1
	s_and_b64 vcc, exec, s[0:1]
	s_waitcnt vmcnt(8)
	v_pk_fma_f32 v[128:129], v[128:129], 0.5, v[152:153] op_sel_hi:[1,0,1]
	v_pk_fma_f32 v[126:127], v[126:127], 0.5, v[150:151] op_sel_hi:[1,0,1]
	v_pk_fma_f32 v[112:113], v[112:113], 0.5, v[166:167] op_sel_hi:[1,0,1]
	v_pk_fma_f32 v[110:111], v[110:111], 0.5, v[164:165] op_sel_hi:[1,0,1]
	global_store_dwordx4 v[146:147], v[110:113], off offset:512
	v_pk_fma_f32 v[108:109], v[108:109], 0.5, v[170:171] op_sel_hi:[1,0,1]
	v_pk_fma_f32 v[106:107], v[106:107], 0.5, v[168:169] op_sel_hi:[1,0,1]
	v_lshl_add_u64 v[110:111], s[48:49], 0, v[220:221]
	global_store_dwordx4 v[146:147], v[106:109], off offset:576
	v_lshl_add_u64 v[110:111], v[110:111], 0, v[142:143]
	v_pk_fma_f32 v[124:125], v[124:125], 0.5, v[162:163] op_sel_hi:[1,0,1]
	v_pk_fma_f32 v[108:109], v[120:121], 0.5, v[174:175] op_sel_hi:[1,0,1]
	v_pk_fma_f32 v[106:107], v[118:119], 0.5, v[172:173] op_sel_hi:[1,0,1]
	v_pk_fma_f32 v[122:123], v[122:123], 0.5, v[160:161] op_sel_hi:[1,0,1]
	global_store_dwordx4 v[110:111], v[106:109], off
	v_pk_fma_f32 v[104:105], v[104:105], 0.5, v[182:183] op_sel_hi:[1,0,1]
	v_pk_fma_f32 v[102:103], v[102:103], 0.5, v[180:181] op_sel_hi:[1,0,1]
	v_pk_fma_f32 v[108:109], v[116:117], 0.5, v[178:179] op_sel_hi:[1,0,1]
	v_pk_fma_f32 v[106:107], v[114:115], 0.5, v[176:177] op_sel_hi:[1,0,1]
	v_pk_fma_f32 v[100:101], v[100:101], 0.5, v[186:187] op_sel_hi:[1,0,1]
	v_pk_fma_f32 v[98:99], v[98:99], 0.5, v[184:185] op_sel_hi:[1,0,1]
	v_lshl_add_u64 v[150:151], v[148:149], 0, s[12:13]
	global_store_dwordx4 v[146:147], v[126:129], off
	global_store_dwordx4 v[146:147], v[122:125], off offset:64
	global_store_dwordx4 v[110:111], v[106:109], off offset:64
	global_store_dwordx4 v[110:111], v[102:105], off offset:512
	global_store_dwordx4 v[110:111], v[98:101], off offset:576
	v_lshl_add_u64 v[146:147], v[148:149], 0, s[14:15]
	v_lshl_add_u64 v[152:153], s[48:49], 0, v[222:223]
	v_lshl_add_u64 v[98:99], v[144:145], 0, v[150:151]
	global_load_dwordx4 v[126:129], v[98:99], off
	global_load_dwordx4 v[122:125], v[98:99], off offset:64
	global_load_dwordx4 v[118:121], v[98:99], off offset:512
	global_load_dwordx4 v[110:113], v[98:99], off offset:576
	v_lshl_add_u64 v[98:99], v[144:145], 0, v[146:147]
	v_lshl_add_u64 v[152:153], v[152:153], 0, v[142:143]
	s_waitcnt vmcnt(12)
; #define ER_LOAD(q, buf) do { _Pragma("unroll") for (int mm = 0; mm < 2; ++mm) { const size_t off_ = (size_t)(row0 + ((q) >> 1) * HALF + (2 * ((q) & 1) + mm) * 16) * ldc + col0; \
;             _Pragma("unroll") for (int bj = 0; bj < 2; ++bj) _Pragma("unroll") for (int n = 0; n < 2; ++n) pre[buf][mm][bj][n] = *(const f32x4*)(base + off_ + bj * HALF + n * 16); } } while (0)
; #define PG8_BAR __builtin_amdgcn_s_barrier()
;     __device__ __forceinline__ void operator()(const f32x4 (&acc)[2][2][4][2], const Unit& u, int wr, int wc, int fr, int fq) const {
;     ...
;         for (int q = 0; q < 4; ++q) {
;             if (q == 0) ER_LOAD(1, 1); else if (q == 1) ER_LOAD(2, 0); else if (q == 2) ER_LOAD(3, 1);
; #pragma unroll
;             for (int mm = 0; mm < 2; ++mm) { const int ai = q >> 1, m = 2 * (q & 1) + mm; const size_t off = (size_t)(row0 + ai * HALF + m * 16) * ldc + col0; float ss = 0.f;
;                 const int rl = wr * 64 + fr + ai * HALF + m * 16, cl0 = col0; const size_t xoff = (size_t)u.pm * ((size_t)ldc * BM) + (size_t)rl * 64;
; #pragma unroll
;                 for (int bj = 0; bj < 2; ++bj)
; #pragma unroll
;                     for (int n = 0; n < 2; ++n) {
;                         const f32x4 o = pre[q & 1][mm][bj][n] + acc[ai][bj][m][n] * scale;
;                         *(f32x4*)(out + off + bj * HALF + n * 16) = o;
; template <class Epi, class Sched, bool ALIGN_EPI = false, bool SP2 = false, bool A_TILED = false>
; __device__ __forceinline__ void gemm_phase(PG8_LAS unsigned char* lds, const Gemm g, const Sched& S, const Epi& E) {
;     ...
;         if constexpr (ALIGN_EPI) { if (wr == 0) PG8_BAR; }
;         if constexpr (!Epi::AFTER_DRAIN) { E(acc, cur, wr, wc, fr, fq); S.done(cur); }
;         if (!has_next) break;
; #pragma unroll
;         for (int a = 0; a < 2; ++a)
; #pragma unroll
;             for (int b = 0; b < 2; ++b)
; #pragma unroll
;                 for (int m = 0; m < 4; ++m)
; #pragma unroll
;                     for (int n = 0; n < 2; ++n) acc[a][b][m][n] = (f32x4){0.f, 0.f, 0.f, 0.f};
;         cur = nxt; cA = nA; cB = nB; ++ui;
;         if constexpr (ALIGN_EPI) { if (wr == 1) PG8_BAR; }
	v_pk_fma_f32 v[80:81], v[80:81], 0.5, v[198:199] op_sel_hi:[1,0,1]
	v_pk_fma_f32 v[78:79], v[78:79], 0.5, v[196:197] op_sel_hi:[1,0,1]
	global_load_dwordx4 v[114:117], v[98:99], off
	global_load_dwordx4 v[106:109], v[98:99], off offset:64
	global_load_dwordx4 v[102:105], v[98:99], off offset:512
	s_nop 0
	global_load_dwordx4 v[98:101], v[98:99], off offset:576
	v_pk_fma_f32 v[76:77], v[76:77], 0.5, v[202:203] op_sel_hi:[1,0,1]
	global_store_dwordx4 v[152:153], v[78:81], off offset:512
	v_pk_fma_f32 v[74:75], v[74:75], 0.5, v[200:201] op_sel_hi:[1,0,1]
	v_pk_fma_f32 v[96:97], v[96:97], 0.5, v[190:191] op_sel_hi:[1,0,1]
	v_lshl_add_u64 v[78:79], s[48:49], 0, v[224:225]
	v_pk_fma_f32 v[94:95], v[94:95], 0.5, v[188:189] op_sel_hi:[1,0,1]
	v_pk_fma_f32 v[92:93], v[92:93], 0.5, v[194:195] op_sel_hi:[1,0,1]
	v_pk_fma_f32 v[90:91], v[90:91], 0.5, v[192:193] op_sel_hi:[1,0,1]
	global_store_dwordx4 v[152:153], v[74:77], off offset:576
	v_lshl_add_u64 v[78:79], v[78:79], 0, v[142:143]
	global_store_dwordx4 v[152:153], v[94:97], off
	v_pk_fma_f32 v[76:77], v[88:89], 0.5, v[206:207] op_sel_hi:[1,0,1]
	v_pk_fma_f32 v[74:75], v[86:87], 0.5, v[204:205] op_sel_hi:[1,0,1]
	global_store_dwordx4 v[152:153], v[90:93], off offset:64
	global_store_dwordx4 v[78:79], v[74:77], off
	v_pk_fma_f32 v[72:73], v[72:73], 0.5, v[214:215] op_sel_hi:[1,0,1]
	v_pk_fma_f32 v[70:71], v[70:71], 0.5, v[212:213] op_sel_hi:[1,0,1]
	v_pk_fma_f32 v[76:77], v[84:85], 0.5, v[210:211] op_sel_hi:[1,0,1]
	v_pk_fma_f32 v[74:75], v[82:83], 0.5, v[208:209] op_sel_hi:[1,0,1]
	v_pk_fma_f32 v[68:69], v[68:69], 0.5, v[218:219] op_sel_hi:[1,0,1]
	v_pk_fma_f32 v[66:67], v[66:67], 0.5, v[216:217] op_sel_hi:[1,0,1]
	v_lshl_add_u64 v[152:153], v[148:149], 0, s[16:17]
	global_store_dwordx4 v[78:79], v[74:77], off offset:64
	global_store_dwordx4 v[78:79], v[70:73], off offset:512
	global_store_dwordx4 v[78:79], v[66:69], off offset:576
	v_lshl_add_u64 v[148:149], v[148:149], 0, s[18:19]
	v_lshl_add_u64 v[94:95], v[144:145], 0, v[148:149]
	v_lshl_add_u64 v[66:67], v[144:145], 0, v[152:153]
	global_load_dwordx4 v[78:81], v[66:67], off
	global_load_dwordx4 v[74:77], v[66:67], off offset:64
	global_load_dwordx4 v[70:73], v[66:67], off offset:512
	s_nop 0
	global_load_dwordx4 v[66:69], v[66:67], off offset:576
	s_nop 0
	global_load_dwordx4 v[90:93], v[94:95], off
	global_load_dwordx4 v[86:89], v[94:95], off offset:64
	global_load_dwordx4 v[82:85], v[94:95], off offset:512
	s_nop 0
	global_load_dwordx4 v[94:97], v[94:95], off offset:576
	s_waitcnt vmcnt(23)
	v_pk_fma_f32 v[62:63], v[62:63], 0.5, v[126:127] op_sel_hi:[1,0,1]
	v_lshl_add_u64 v[126:127], s[48:49], 0, v[150:151]
	v_lshl_add_u64 v[126:127], v[126:127], 0, v[142:143]
	s_waitcnt vmcnt(21)
	v_pk_fma_f32 v[52:53], v[52:53], 0.5, v[120:121] op_sel_hi:[1,0,1]
	v_pk_fma_f32 v[50:51], v[50:51], 0.5, v[118:119] op_sel_hi:[1,0,1]
	global_store_dwordx4 v[126:127], v[50:53], off offset:512
	s_waitcnt vmcnt(21)
	v_pk_fma_f32 v[44:45], v[44:45], 0.5, v[112:113] op_sel_hi:[1,0,1]
	s_waitcnt vmcnt(18)
	v_pk_fma_f32 v[36:37], v[36:37], 0.5, v[104:105] op_sel_hi:[1,0,1]
	v_lshl_add_u64 v[50:51], s[48:49], 0, v[146:147]
	v_lshl_add_u64 v[50:51], v[50:51], 0, v[142:143]
	v_pk_fma_f32 v[34:35], v[34:35], 0.5, v[102:103] op_sel_hi:[1,0,1]
	global_store_dwordx4 v[50:51], v[34:37], off offset:512
	v_pk_fma_f32 v[42:43], v[42:43], 0.5, v[110:111] op_sel_hi:[1,0,1]
	s_waitcnt vmcnt(18)
	v_pk_fma_f32 v[28:29], v[28:29], 0.5, v[100:101] op_sel_hi:[1,0,1]
	v_lshl_add_u64 v[34:35], s[48:49], 0, v[152:153]
	v_lshl_add_u64 v[34:35], v[34:35], 0, v[142:143]
	v_pk_fma_f32 v[26:27], v[26:27], 0.5, v[98:99] op_sel_hi:[1,0,1]
	global_store_dwordx4 v[126:127], v[42:45], off offset:576
	global_store_dwordx4 v[50:51], v[26:29], off offset:576
	v_pk_fma_f32 v[64:65], v[64:65], 0.5, v[128:129] op_sel_hi:[1,0,1]
	v_pk_fma_f32 v[44:45], v[56:57], 0.5, v[116:117] op_sel_hi:[1,0,1]
	v_pk_fma_f32 v[42:43], v[54:55], 0.5, v[114:115] op_sel_hi:[1,0,1]
	v_pk_fma_f32 v[60:61], v[60:61], 0.5, v[124:125] op_sel_hi:[1,0,1]
	v_pk_fma_f32 v[58:59], v[58:59], 0.5, v[122:123] op_sel_hi:[1,0,1]
	global_store_dwordx4 v[50:51], v[42:45], off
	global_store_dwordx4 v[126:127], v[62:65], off
	global_store_dwordx4 v[126:127], v[58:61], off offset:64
	v_pk_fma_f32 v[44:45], v[48:49], 0.5, v[108:109] op_sel_hi:[1,0,1]
	v_pk_fma_f32 v[42:43], v[46:47], 0.5, v[106:107] op_sel_hi:[1,0,1]
	global_store_dwordx4 v[50:51], v[42:45], off offset:64
	s_waitcnt vmcnt(15)
	v_pk_fma_f32 v[28:29], v[40:41], 0.5, v[80:81] op_sel_hi:[1,0,1]
	v_pk_fma_f32 v[26:27], v[38:39], 0.5, v[78:79] op_sel_hi:[1,0,1]
	s_waitcnt vmcnt(13)
	v_pk_fma_f32 v[20:21], v[20:21], 0.5, v[72:73] op_sel_hi:[1,0,1]
	v_pk_fma_f32 v[18:19], v[18:19], 0.5, v[70:71] op_sel_hi:[1,0,1]
	global_store_dwordx4 v[34:35], v[18:21], off offset:512
	s_waitcnt vmcnt(13)
	v_pk_fma_f32 v[12:13], v[12:13], 0.5, v[68:69] op_sel_hi:[1,0,1]
	v_pk_fma_f32 v[10:11], v[10:11], 0.5, v[66:67] op_sel_hi:[1,0,1]
	v_lshl_add_u64 v[18:19], s[48:49], 0, v[148:149]
	global_store_dwordx4 v[34:35], v[10:13], off offset:576
	v_lshl_add_u64 v[18:19], v[18:19], 0, v[142:143]
	global_store_dwordx4 v[34:35], v[26:29], off
	s_waitcnt vmcnt(14)
	v_pk_fma_f32 v[12:13], v[24:25], 0.5, v[92:93] op_sel_hi:[1,0,1]
	v_pk_fma_f32 v[10:11], v[22:23], 0.5, v[90:91] op_sel_hi:[1,0,1]
	v_pk_fma_f32 v[28:29], v[32:33], 0.5, v[76:77] op_sel_hi:[1,0,1]
	v_pk_fma_f32 v[26:27], v[30:31], 0.5, v[74:75] op_sel_hi:[1,0,1]
	global_store_dwordx4 v[18:19], v[10:13], off
	s_waitcnt vmcnt(13)
	v_pk_fma_f32 v[8:9], v[8:9], 0.5, v[84:85] op_sel_hi:[1,0,1]
	v_pk_fma_f32 v[6:7], v[6:7], 0.5, v[82:83] op_sel_hi:[1,0,1]
	v_pk_fma_f32 v[12:13], v[16:17], 0.5, v[88:89] op_sel_hi:[1,0,1]
	v_pk_fma_f32 v[10:11], v[14:15], 0.5, v[86:87] op_sel_hi:[1,0,1]
	s_waitcnt vmcnt(12)
	v_pk_fma_f32 v[4:5], v[4:5], 0.5, v[96:97] op_sel_hi:[1,0,1]
	v_pk_fma_f32 v[2:3], v[2:3], 0.5, v[94:95] op_sel_hi:[1,0,1]
	global_store_dwordx4 v[34:35], v[26:29], off offset:64
	global_store_dwordx4 v[18:19], v[10:13], off offset:64
	global_store_dwordx4 v[18:19], v[6:9], off offset:512
	global_store_dwordx4 v[18:19], v[2:5], off offset:576
	s_cbranch_vccnz .LBB0_1235
	s_andn2_b64 vcc, exec, s[8:9]
	s_cbranch_vccnz .LBB0_1234
	s_barrier
	s_branch .LBB0_1234
